# compression MLP K loop rewritten by hand: W1 K-slabs shared by the 8 waves through LDS (LDS-DMA, double buffered), pos table in LDS, activations prefetched 4 steps ahead
# speedup vs baseline: 1.0612x; 1.0068x over previous
.LBB0_732:
	s_and_b32 s29, s28, 3
	s_cmpk_gt_u32 s28, 0x7f
	s_cselect_b64 s[20:21], -1, 0
	s_cmpk_lt_u32 s28, 0x80
	s_cselect_b64 s[22:23], -1, 0
	s_and_b64 s[0:1], s[22:23], exec
	s_mov_b32 s0, 0x4d00000
	s_cselect_b32 s0, s0, 0x4d80000
	s_movk_i32 s1, 0xb8
	v_readlane_b32 s2, v251, 22
	s_cselect_b32 s1, s1, 0xc0
	v_readlane_b32 s3, v251, 23
	s_add_u32 s2, s2, s0
	s_addc_u32 s3, s3, 0
	s_add_u32 s24, s48, s1
	s_addc_u32 s25, s49, 0
	s_ashr_i32 s1, s28, 5
	s_and_b32 s1, s1, -4
	s_or_b32 s30, s1, s29
	s_ashr_i32 s31, s30, 31
	s_lshl_b64 s[30:31], s[30:31], 23
	s_add_u32 s1, s26, s30
	s_addc_u32 s29, s27, s31
	s_lshl_b32 s30, s28, 16
	s_and_b32 s30, s30, 0x7c0000
	s_load_dwordx2 s[24:25], s[24:25], 0x0
	s_add_u32 s30, s1, s30
	s_addc_u32 s31, s29, 0
	v_lshlrev_b32_e32 v96, 1, v124
	v_lshl_add_u64 v[178:179], s[30:31], 0, v[96:97]
	v_readlane_b32 s29, v251, 26
	v_lshlrev_b32_e32 v118, 12, v170
	s_and_b32 s30, s29, 1
	s_lshl_b32 s30, s30, 18
	s_lshr_b32 s31, s29, 1
	s_lshl_b32 s31, s31, 4
	s_add_i32 s30, s30, s31
	v_add_u32_e32 v118, s30, v118
	v_and_b32_e32 v119, 15, v170
	v_lshrrev_b32_e32 v120, 4, v170
	v_lshlrev_b32_e32 v119, 4, v119
	v_lshl_add_u32 v119, v120, 11, v119
	v_lshlrev_b32_e32 v120, 5, v120
	v_add_u32_e32 v120, 0x20000, v120
	v_mov_b32_e32 v121, v125
	s_lshl_b32 s31, s29, 10
	v_mov_b32_e32 v72, 0
	v_mov_b32_e32 v73, 0
	v_mov_b32_e32 v74, 0
	v_mov_b32_e32 v75, 0
	v_mov_b32_e32 v24, 0
	v_mov_b32_e32 v25, 0
	v_mov_b32_e32 v26, 0
	v_mov_b32_e32 v27, 0
	v_mov_b32_e32 v20, 0
	v_mov_b32_e32 v21, 0
	v_mov_b32_e32 v22, 0
	v_mov_b32_e32 v23, 0
	v_mov_b32_e32 v16, 0
	v_mov_b32_e32 v17, 0
	v_mov_b32_e32 v18, 0
	v_mov_b32_e32 v19, 0
	v_mov_b32_e32 v12, 0
	v_mov_b32_e32 v13, 0
	v_mov_b32_e32 v14, 0
	v_mov_b32_e32 v15, 0
	v_mov_b32_e32 v8, 0
	v_mov_b32_e32 v9, 0
	v_mov_b32_e32 v10, 0
	v_mov_b32_e32 v11, 0
	v_mov_b32_e32 v4, 0
	v_mov_b32_e32 v5, 0
	v_mov_b32_e32 v6, 0
	v_mov_b32_e32 v7, 0
	v_mov_b32_e32 v0, 0
	v_mov_b32_e32 v1, 0
	v_mov_b32_e32 v2, 0
	v_mov_b32_e32 v3, 0
	s_waitcnt lgkmcnt(0)
	s_barrier
	v_lshl_add_u32 v184, s29, 6, v170
	v_lshlrev_b32_e32 v184, 4, v184
	global_load_dwordx4 v[98:101], v184, s[24:25]
	v_add_u32_e32 v182, 0, v121
	v_min_i32_e32 v182, 0x7ff, v182
	v_lshlrev_b32_e32 v182, 7, v182
	v_mov_b32_e32 v183, 0
	v_lshl_add_u64 v[180:181], v[178:179], 0, v[182:183]
	global_load_dwordx4 v[28:31], v[180:181], off
	global_load_dwordx4 v[32:35], v[180:181], off offset:64
	v_add_u32_e32 v182, 1, v121
	v_min_i32_e32 v182, 0x7ff, v182
	v_lshlrev_b32_e32 v182, 7, v182
	v_mov_b32_e32 v183, 0
	v_lshl_add_u64 v[180:181], v[178:179], 0, v[182:183]
	global_load_dwordx4 v[36:39], v[180:181], off
	global_load_dwordx4 v[40:43], v[180:181], off offset:64
	s_mov_b64 s[0:1], s[2:3]
	s_add_i32 s100, s31, 0
	s_add_i32 m0, s100, 0x0
	s_nop 0
	global_load_lds_dwordx4 v118, s[0:1]
	s_add_i32 m0, s100, 0x2000
	s_add_u32 s0, s0, 64
	s_addc_u32 s1, s1, 0
	global_load_lds_dwordx4 v118, s[0:1]
	s_add_i32 m0, s100, 0x4000
	s_add_u32 s0, s0, 64
	s_addc_u32 s1, s1, 0
	global_load_lds_dwordx4 v118, s[0:1]
	s_add_i32 m0, s100, 0x6000
	s_add_u32 s0, s0, 64
	s_addc_u32 s1, s1, 0
	global_load_lds_dwordx4 v118, s[0:1]
	s_add_i32 m0, s100, 0x8000
	s_add_u32 s0, s0, 64
	s_addc_u32 s1, s1, 0
	global_load_lds_dwordx4 v118, s[0:1]
	s_add_i32 m0, s100, 0xa000
	s_add_u32 s0, s0, 64
	s_addc_u32 s1, s1, 0
	global_load_lds_dwordx4 v118, s[0:1]
	s_add_i32 m0, s100, 0xc000
	s_add_u32 s0, s0, 64
	s_addc_u32 s1, s1, 0
	global_load_lds_dwordx4 v118, s[0:1]
	s_add_i32 m0, s100, 0xe000
	s_add_u32 s0, s0, 64
	s_addc_u32 s1, s1, 0
	global_load_lds_dwordx4 v118, s[0:1]
	s_waitcnt vmcnt(0)
	v_add_u32_e32 v184, 0x20000, v184
	ds_write_b128 v184, v[98:101]
	s_waitcnt lgkmcnt(0)
	s_barrier
	s_mov_b32 s29, 0
	s_mov_b32 s30, 0
.Lcw1_slab:
	v_add_u32_e32 v185, s30, v119
	s_lshl_b32 s101, s29, 10
	v_add_u32_e32 v186, s101, v120
	v_add_u32_e32 v182, 2, v121
	v_min_i32_e32 v182, 0x7ff, v182
	v_lshlrev_b32_e32 v182, 7, v182
	v_mov_b32_e32 v183, 0
	v_lshl_add_u64 v[180:181], v[178:179], 0, v[182:183]
	global_load_dwordx4 v[44:47], v[180:181], off
	global_load_dwordx4 v[48:51], v[180:181], off offset:64
	v_add_u32_e32 v182, 3, v121
	v_min_i32_e32 v182, 0x7ff, v182
	v_lshlrev_b32_e32 v182, 7, v182
	v_mov_b32_e32 v183, 0
	v_lshl_add_u64 v[180:181], v[178:179], 0, v[182:183]
	global_load_dwordx4 v[52:55], v[180:181], off
	global_load_dwordx4 v[56:59], v[180:181], off offset:64
	s_cmp_eq_u32 s29, 7
	s_cbranch_scc1 .Lcw1_nodma
	s_add_i32 s101, s29, 1
	s_lshl_b32 s101, s101, 9
	s_add_u32 s0, s2, s101
	s_addc_u32 s1, s3, 0
	s_xor_b32 s100, s30, 0x10000
	s_add_i32 s100, s100, s31
	s_add_i32 m0, s100, 0x0
	s_nop 0
	global_load_lds_dwordx4 v118, s[0:1]
	s_add_i32 m0, s100, 0x2000
	s_add_u32 s0, s0, 64
	s_addc_u32 s1, s1, 0
	global_load_lds_dwordx4 v118, s[0:1]
	s_add_i32 m0, s100, 0x4000
	s_add_u32 s0, s0, 64
	s_addc_u32 s1, s1, 0
	global_load_lds_dwordx4 v118, s[0:1]
	s_add_i32 m0, s100, 0x6000
	s_add_u32 s0, s0, 64
	s_addc_u32 s1, s1, 0
	global_load_lds_dwordx4 v118, s[0:1]
	s_add_i32 m0, s100, 0x8000
	s_add_u32 s0, s0, 64
	s_addc_u32 s1, s1, 0
	global_load_lds_dwordx4 v118, s[0:1]
	s_add_i32 m0, s100, 0xa000
	s_add_u32 s0, s0, 64
	s_addc_u32 s1, s1, 0
	global_load_lds_dwordx4 v118, s[0:1]
	s_add_i32 m0, s100, 0xc000
	s_add_u32 s0, s0, 64
	s_addc_u32 s1, s1, 0
	global_load_lds_dwordx4 v118, s[0:1]
	s_add_i32 m0, s100, 0xe000
	s_add_u32 s0, s0, 64
	s_addc_u32 s1, s1, 0
	global_load_lds_dwordx4 v118, s[0:1]
.Lcw1_nodma:
	ds_read_b128 v[60:63], v185 offset:0
	ds_read_b128 v[64:67], v185 offset:256
	ds_read_b128 v[68:71], v185 offset:512
	ds_read_b128 v[76:79], v185 offset:768
	ds_read_b128 v[80:83], v185 offset:1024
	ds_read_b128 v[84:87], v185 offset:1280
	ds_read_b128 v[88:91], v185 offset:1536
	ds_read_b128 v[92:95], v185 offset:1792
	ds_read_b128 v[98:101], v186 offset:0
	ds_read_b128 v[102:105], v186 offset:16
	v_lshlrev_b32_e32 v110, 16, v28
	v_and_b32_e32 v111, 0xffff0000, v28
	v_lshlrev_b32_e32 v112, 16, v29
	v_and_b32_e32 v113, 0xffff0000, v29
	v_lshlrev_b32_e32 v114, 16, v30
	v_and_b32_e32 v115, 0xffff0000, v30
	v_lshlrev_b32_e32 v116, 16, v31
	v_and_b32_e32 v117, 0xffff0000, v31
	s_waitcnt lgkmcnt(0)
	v_pk_add_f32 v[110:111], v[98:99], v[110:111]
	v_pk_add_f32 v[112:113], v[100:101], v[112:113]
	v_pk_add_f32 v[114:115], v[102:103], v[114:115]
	v_pk_add_f32 v[116:117], v[104:105], v[116:117]
	v_cvt_pk_bf16_f32 v106, v110, v111
	v_cvt_pk_bf16_f32 v107, v112, v113
	v_cvt_pk_bf16_f32 v108, v114, v115
	v_cvt_pk_bf16_f32 v109, v116, v117
	s_nop 1
	v_mfma_f32_16x16x32_bf16 v[72:75], v[106:109], v[60:63], v[72:75]
	v_mfma_f32_16x16x32_bf16 v[24:27], v[106:109], v[64:67], v[24:27]
	v_mfma_f32_16x16x32_bf16 v[20:23], v[106:109], v[68:71], v[20:23]
	v_mfma_f32_16x16x32_bf16 v[16:19], v[106:109], v[76:79], v[16:19]
	v_mfma_f32_16x16x32_bf16 v[12:15], v[106:109], v[80:83], v[12:15]
	v_mfma_f32_16x16x32_bf16 v[8:11], v[106:109], v[84:87], v[8:11]
	v_mfma_f32_16x16x32_bf16 v[4:7], v[106:109], v[88:91], v[4:7]
	v_mfma_f32_16x16x32_bf16 v[0:3], v[106:109], v[92:95], v[0:3]
	ds_read_b128 v[60:63], v185 offset:8192
	ds_read_b128 v[64:67], v185 offset:8448
	ds_read_b128 v[68:71], v185 offset:8704
	ds_read_b128 v[76:79], v185 offset:8960
	ds_read_b128 v[80:83], v185 offset:9216
	ds_read_b128 v[84:87], v185 offset:9472
	ds_read_b128 v[88:91], v185 offset:9728
	ds_read_b128 v[92:95], v185 offset:9984
	ds_read_b128 v[98:101], v186 offset:128
	ds_read_b128 v[102:105], v186 offset:144
	v_lshlrev_b32_e32 v110, 16, v32
	v_and_b32_e32 v111, 0xffff0000, v32
	v_lshlrev_b32_e32 v112, 16, v33
	v_and_b32_e32 v113, 0xffff0000, v33
	v_lshlrev_b32_e32 v114, 16, v34
	v_and_b32_e32 v115, 0xffff0000, v34
	v_lshlrev_b32_e32 v116, 16, v35
	v_and_b32_e32 v117, 0xffff0000, v35
	s_waitcnt lgkmcnt(0)
	v_pk_add_f32 v[110:111], v[98:99], v[110:111]
	v_pk_add_f32 v[112:113], v[100:101], v[112:113]
	v_pk_add_f32 v[114:115], v[102:103], v[114:115]
	v_pk_add_f32 v[116:117], v[104:105], v[116:117]
	v_cvt_pk_bf16_f32 v106, v110, v111
	v_cvt_pk_bf16_f32 v107, v112, v113
	v_cvt_pk_bf16_f32 v108, v114, v115
	v_cvt_pk_bf16_f32 v109, v116, v117
	s_nop 1
	v_mfma_f32_16x16x32_bf16 v[72:75], v[106:109], v[60:63], v[72:75]
	v_mfma_f32_16x16x32_bf16 v[24:27], v[106:109], v[64:67], v[24:27]
	v_mfma_f32_16x16x32_bf16 v[20:23], v[106:109], v[68:71], v[20:23]
	v_mfma_f32_16x16x32_bf16 v[16:19], v[106:109], v[76:79], v[16:19]
	v_mfma_f32_16x16x32_bf16 v[12:15], v[106:109], v[80:83], v[12:15]
	v_mfma_f32_16x16x32_bf16 v[8:11], v[106:109], v[84:87], v[8:11]
	v_mfma_f32_16x16x32_bf16 v[4:7], v[106:109], v[88:91], v[4:7]
	v_mfma_f32_16x16x32_bf16 v[0:3], v[106:109], v[92:95], v[0:3]
	ds_read_b128 v[60:63], v185 offset:16384
	ds_read_b128 v[64:67], v185 offset:16640
	ds_read_b128 v[68:71], v185 offset:16896
	ds_read_b128 v[76:79], v185 offset:17152
	ds_read_b128 v[80:83], v185 offset:17408
	ds_read_b128 v[84:87], v185 offset:17664
	ds_read_b128 v[88:91], v185 offset:17920
	ds_read_b128 v[92:95], v185 offset:18176
	ds_read_b128 v[98:101], v186 offset:256
	ds_read_b128 v[102:105], v186 offset:272
	v_lshlrev_b32_e32 v110, 16, v36
	v_and_b32_e32 v111, 0xffff0000, v36
	v_lshlrev_b32_e32 v112, 16, v37
	v_and_b32_e32 v113, 0xffff0000, v37
	v_lshlrev_b32_e32 v114, 16, v38
	v_and_b32_e32 v115, 0xffff0000, v38
	v_lshlrev_b32_e32 v116, 16, v39
	v_and_b32_e32 v117, 0xffff0000, v39
	s_waitcnt lgkmcnt(0)
	v_pk_add_f32 v[110:111], v[98:99], v[110:111]
	v_pk_add_f32 v[112:113], v[100:101], v[112:113]
	v_pk_add_f32 v[114:115], v[102:103], v[114:115]
	v_pk_add_f32 v[116:117], v[104:105], v[116:117]
	v_cvt_pk_bf16_f32 v106, v110, v111
	v_cvt_pk_bf16_f32 v107, v112, v113
	v_cvt_pk_bf16_f32 v108, v114, v115
	v_cvt_pk_bf16_f32 v109, v116, v117
	s_nop 1
	v_mfma_f32_16x16x32_bf16 v[72:75], v[106:109], v[60:63], v[72:75]
	v_mfma_f32_16x16x32_bf16 v[24:27], v[106:109], v[64:67], v[24:27]
	v_mfma_f32_16x16x32_bf16 v[20:23], v[106:109], v[68:71], v[20:23]
	v_mfma_f32_16x16x32_bf16 v[16:19], v[106:109], v[76:79], v[16:19]
	v_mfma_f32_16x16x32_bf16 v[12:15], v[106:109], v[80:83], v[12:15]
	v_mfma_f32_16x16x32_bf16 v[8:11], v[106:109], v[84:87], v[8:11]
	v_mfma_f32_16x16x32_bf16 v[4:7], v[106:109], v[88:91], v[4:7]
	v_mfma_f32_16x16x32_bf16 v[0:3], v[106:109], v[92:95], v[0:3]
	ds_read_b128 v[60:63], v185 offset:24576
	ds_read_b128 v[64:67], v185 offset:24832
	ds_read_b128 v[68:71], v185 offset:25088
	ds_read_b128 v[76:79], v185 offset:25344
	ds_read_b128 v[80:83], v185 offset:25600
	ds_read_b128 v[84:87], v185 offset:25856
	ds_read_b128 v[88:91], v185 offset:26112
	ds_read_b128 v[92:95], v185 offset:26368
	ds_read_b128 v[98:101], v186 offset:384
	ds_read_b128 v[102:105], v186 offset:400
	v_lshlrev_b32_e32 v110, 16, v40
	v_and_b32_e32 v111, 0xffff0000, v40
	v_lshlrev_b32_e32 v112, 16, v41
	v_and_b32_e32 v113, 0xffff0000, v41
	v_lshlrev_b32_e32 v114, 16, v42
	v_and_b32_e32 v115, 0xffff0000, v42
	v_lshlrev_b32_e32 v116, 16, v43
	v_and_b32_e32 v117, 0xffff0000, v43
	s_waitcnt lgkmcnt(0)
	v_pk_add_f32 v[110:111], v[98:99], v[110:111]
	v_pk_add_f32 v[112:113], v[100:101], v[112:113]
	v_pk_add_f32 v[114:115], v[102:103], v[114:115]
	v_pk_add_f32 v[116:117], v[104:105], v[116:117]
	v_cvt_pk_bf16_f32 v106, v110, v111
	v_cvt_pk_bf16_f32 v107, v112, v113
	v_cvt_pk_bf16_f32 v108, v114, v115
	v_cvt_pk_bf16_f32 v109, v116, v117
	s_nop 1
	v_mfma_f32_16x16x32_bf16 v[72:75], v[106:109], v[60:63], v[72:75]
	v_mfma_f32_16x16x32_bf16 v[24:27], v[106:109], v[64:67], v[24:27]
	v_mfma_f32_16x16x32_bf16 v[20:23], v[106:109], v[68:71], v[20:23]
	v_mfma_f32_16x16x32_bf16 v[16:19], v[106:109], v[76:79], v[16:19]
	v_mfma_f32_16x16x32_bf16 v[12:15], v[106:109], v[80:83], v[12:15]
	v_mfma_f32_16x16x32_bf16 v[8:11], v[106:109], v[84:87], v[8:11]
	v_mfma_f32_16x16x32_bf16 v[4:7], v[106:109], v[88:91], v[4:7]
	v_mfma_f32_16x16x32_bf16 v[0:3], v[106:109], v[92:95], v[0:3]
	s_cmp_eq_u32 s29, 7
	s_cbranch_scc1 .Lcw1_mid7
	s_waitcnt vmcnt(8)
	v_add_u32_e32 v121, 4, v121
	v_add_u32_e32 v182, 0, v121
	v_min_i32_e32 v182, 0x7ff, v182
	v_lshlrev_b32_e32 v182, 7, v182
	v_mov_b32_e32 v183, 0
	v_lshl_add_u64 v[180:181], v[178:179], 0, v[182:183]
	global_load_dwordx4 v[28:31], v[180:181], off
	global_load_dwordx4 v[32:35], v[180:181], off offset:64
	v_add_u32_e32 v182, 1, v121
	v_min_i32_e32 v182, 0x7ff, v182
	v_lshlrev_b32_e32 v182, 7, v182
	v_mov_b32_e32 v183, 0
	v_lshl_add_u64 v[180:181], v[178:179], 0, v[182:183]
	global_load_dwordx4 v[36:39], v[180:181], off
	global_load_dwordx4 v[40:43], v[180:181], off offset:64
	v_add_u32_e32 v121, -4, v121
	s_branch .Lcw1_mid

.Lcw1_mid:
	ds_read_b128 v[60:63], v185 offset:32768
	ds_read_b128 v[64:67], v185 offset:33024
	ds_read_b128 v[68:71], v185 offset:33280
	ds_read_b128 v[76:79], v185 offset:33536
	ds_read_b128 v[80:83], v185 offset:33792
	ds_read_b128 v[84:87], v185 offset:34048
	ds_read_b128 v[88:91], v185 offset:34304
	ds_read_b128 v[92:95], v185 offset:34560
	ds_read_b128 v[98:101], v186 offset:512
	ds_read_b128 v[102:105], v186 offset:528
	v_lshlrev_b32_e32 v110, 16, v44
	v_and_b32_e32 v111, 0xffff0000, v44
	v_lshlrev_b32_e32 v112, 16, v45
	v_and_b32_e32 v113, 0xffff0000, v45
	v_lshlrev_b32_e32 v114, 16, v46
	v_and_b32_e32 v115, 0xffff0000, v46
	v_lshlrev_b32_e32 v116, 16, v47
	v_and_b32_e32 v117, 0xffff0000, v47
	s_waitcnt lgkmcnt(0)
	v_pk_add_f32 v[110:111], v[98:99], v[110:111]
	v_pk_add_f32 v[112:113], v[100:101], v[112:113]
	v_pk_add_f32 v[114:115], v[102:103], v[114:115]
	v_pk_add_f32 v[116:117], v[104:105], v[116:117]
	v_cvt_pk_bf16_f32 v106, v110, v111
	v_cvt_pk_bf16_f32 v107, v112, v113
	v_cvt_pk_bf16_f32 v108, v114, v115
	v_cvt_pk_bf16_f32 v109, v116, v117
	s_nop 1
	v_mfma_f32_16x16x32_bf16 v[72:75], v[106:109], v[60:63], v[72:75]
	v_mfma_f32_16x16x32_bf16 v[24:27], v[106:109], v[64:67], v[24:27]
	v_mfma_f32_16x16x32_bf16 v[20:23], v[106:109], v[68:71], v[20:23]
	v_mfma_f32_16x16x32_bf16 v[16:19], v[106:109], v[76:79], v[16:19]
	v_mfma_f32_16x16x32_bf16 v[12:15], v[106:109], v[80:83], v[12:15]
	v_mfma_f32_16x16x32_bf16 v[8:11], v[106:109], v[84:87], v[8:11]
	v_mfma_f32_16x16x32_bf16 v[4:7], v[106:109], v[88:91], v[4:7]
	v_mfma_f32_16x16x32_bf16 v[0:3], v[106:109], v[92:95], v[0:3]
	ds_read_b128 v[60:63], v185 offset:40960
	ds_read_b128 v[64:67], v185 offset:41216
	ds_read_b128 v[68:71], v185 offset:41472
	ds_read_b128 v[76:79], v185 offset:41728
	ds_read_b128 v[80:83], v185 offset:41984
	ds_read_b128 v[84:87], v185 offset:42240
	ds_read_b128 v[88:91], v185 offset:42496
	ds_read_b128 v[92:95], v185 offset:42752
	ds_read_b128 v[98:101], v186 offset:640
	ds_read_b128 v[102:105], v186 offset:656
	v_lshlrev_b32_e32 v110, 16, v48
	v_and_b32_e32 v111, 0xffff0000, v48
	v_lshlrev_b32_e32 v112, 16, v49
	v_and_b32_e32 v113, 0xffff0000, v49
	v_lshlrev_b32_e32 v114, 16, v50
	v_and_b32_e32 v115, 0xffff0000, v50
	v_lshlrev_b32_e32 v116, 16, v51
	v_and_b32_e32 v117, 0xffff0000, v51
	s_waitcnt lgkmcnt(0)
	v_pk_add_f32 v[110:111], v[98:99], v[110:111]
	v_pk_add_f32 v[112:113], v[100:101], v[112:113]
	v_pk_add_f32 v[114:115], v[102:103], v[114:115]
	v_pk_add_f32 v[116:117], v[104:105], v[116:117]
	v_cvt_pk_bf16_f32 v106, v110, v111
	v_cvt_pk_bf16_f32 v107, v112, v113
	v_cvt_pk_bf16_f32 v108, v114, v115
	v_cvt_pk_bf16_f32 v109, v116, v117
	s_nop 1
	v_mfma_f32_16x16x32_bf16 v[72:75], v[106:109], v[60:63], v[72:75]
	v_mfma_f32_16x16x32_bf16 v[24:27], v[106:109], v[64:67], v[24:27]
	v_mfma_f32_16x16x32_bf16 v[20:23], v[106:109], v[68:71], v[20:23]
	v_mfma_f32_16x16x32_bf16 v[16:19], v[106:109], v[76:79], v[16:19]
	v_mfma_f32_16x16x32_bf16 v[12:15], v[106:109], v[80:83], v[12:15]
	v_mfma_f32_16x16x32_bf16 v[8:11], v[106:109], v[84:87], v[8:11]
	v_mfma_f32_16x16x32_bf16 v[4:7], v[106:109], v[88:91], v[4:7]
	v_mfma_f32_16x16x32_bf16 v[0:3], v[106:109], v[92:95], v[0:3]
	ds_read_b128 v[60:63], v185 offset:49152
	ds_read_b128 v[64:67], v185 offset:49408
	ds_read_b128 v[68:71], v185 offset:49664
	ds_read_b128 v[76:79], v185 offset:49920
	ds_read_b128 v[80:83], v185 offset:50176
	ds_read_b128 v[84:87], v185 offset:50432
	ds_read_b128 v[88:91], v185 offset:50688
	ds_read_b128 v[92:95], v185 offset:50944
	ds_read_b128 v[98:101], v186 offset:768
	ds_read_b128 v[102:105], v186 offset:784
	v_lshlrev_b32_e32 v110, 16, v52
	v_and_b32_e32 v111, 0xffff0000, v52
	v_lshlrev_b32_e32 v112, 16, v53
	v_and_b32_e32 v113, 0xffff0000, v53
	v_lshlrev_b32_e32 v114, 16, v54
	v_and_b32_e32 v115, 0xffff0000, v54
	v_lshlrev_b32_e32 v116, 16, v55
	v_and_b32_e32 v117, 0xffff0000, v55
	s_waitcnt lgkmcnt(0)
	v_pk_add_f32 v[110:111], v[98:99], v[110:111]
	v_pk_add_f32 v[112:113], v[100:101], v[112:113]
	v_pk_add_f32 v[114:115], v[102:103], v[114:115]
	v_pk_add_f32 v[116:117], v[104:105], v[116:117]
	v_cvt_pk_bf16_f32 v106, v110, v111
	v_cvt_pk_bf16_f32 v107, v112, v113
	v_cvt_pk_bf16_f32 v108, v114, v115
	v_cvt_pk_bf16_f32 v109, v116, v117
	s_nop 1
	v_mfma_f32_16x16x32_bf16 v[72:75], v[106:109], v[60:63], v[72:75]
	v_mfma_f32_16x16x32_bf16 v[24:27], v[106:109], v[64:67], v[24:27]
	v_mfma_f32_16x16x32_bf16 v[20:23], v[106:109], v[68:71], v[20:23]
	v_mfma_f32_16x16x32_bf16 v[16:19], v[106:109], v[76:79], v[16:19]
	v_mfma_f32_16x16x32_bf16 v[12:15], v[106:109], v[80:83], v[12:15]
	v_mfma_f32_16x16x32_bf16 v[8:11], v[106:109], v[84:87], v[8:11]
	v_mfma_f32_16x16x32_bf16 v[4:7], v[106:109], v[88:91], v[4:7]
	v_mfma_f32_16x16x32_bf16 v[0:3], v[106:109], v[92:95], v[0:3]
	ds_read_b128 v[60:63], v185 offset:57344
	ds_read_b128 v[64:67], v185 offset:57600
	ds_read_b128 v[68:71], v185 offset:57856
	ds_read_b128 v[76:79], v185 offset:58112
	ds_read_b128 v[80:83], v185 offset:58368
	ds_read_b128 v[84:87], v185 offset:58624
	ds_read_b128 v[88:91], v185 offset:58880
	ds_read_b128 v[92:95], v185 offset:59136
	ds_read_b128 v[98:101], v186 offset:896
	ds_read_b128 v[102:105], v186 offset:912
	v_lshlrev_b32_e32 v110, 16, v56
	v_and_b32_e32 v111, 0xffff0000, v56
	v_lshlrev_b32_e32 v112, 16, v57
	v_and_b32_e32 v113, 0xffff0000, v57
	v_lshlrev_b32_e32 v114, 16, v58
	v_and_b32_e32 v115, 0xffff0000, v58
	v_lshlrev_b32_e32 v116, 16, v59
	v_and_b32_e32 v117, 0xffff0000, v59
	s_waitcnt lgkmcnt(0)
	v_pk_add_f32 v[110:111], v[98:99], v[110:111]
	v_pk_add_f32 v[112:113], v[100:101], v[112:113]
	v_pk_add_f32 v[114:115], v[102:103], v[114:115]
	v_pk_add_f32 v[116:117], v[104:105], v[116:117]
	v_cvt_pk_bf16_f32 v106, v110, v111
	v_cvt_pk_bf16_f32 v107, v112, v113
	v_cvt_pk_bf16_f32 v108, v114, v115
	v_cvt_pk_bf16_f32 v109, v116, v117
	s_nop 1
	v_mfma_f32_16x16x32_bf16 v[72:75], v[106:109], v[60:63], v[72:75]
	v_mfma_f32_16x16x32_bf16 v[24:27], v[106:109], v[64:67], v[24:27]
	v_mfma_f32_16x16x32_bf16 v[20:23], v[106:109], v[68:71], v[20:23]
	v_mfma_f32_16x16x32_bf16 v[16:19], v[106:109], v[76:79], v[16:19]
	v_mfma_f32_16x16x32_bf16 v[12:15], v[106:109], v[80:83], v[12:15]
	v_mfma_f32_16x16x32_bf16 v[8:11], v[106:109], v[84:87], v[8:11]
	v_mfma_f32_16x16x32_bf16 v[4:7], v[106:109], v[88:91], v[4:7]
	v_mfma_f32_16x16x32_bf16 v[0:3], v[106:109], v[92:95], v[0:3]
	s_waitcnt vmcnt(0)
	s_barrier
	v_add_u32_e32 v121, 4, v121
	s_xor_b32 s30, s30, 0x10000
	s_add_i32 s29, s29, 1
	s_cmp_lt_u32 s29, 8
	s_cbranch_scc1 .Lcw1_slab
	s_nop 7
